# v91 + one static s_setprio 1 at kernel entry for waves 0-3 (older / leading half), kept for the whole kernel
# speedup vs baseline: 1.0055x; 1.0055x over previous
; #define LAS __attribute__((address_space(3)))
; __global__ void __launch_bounds__(NW * 64, 2) fwd_kernel(Args a) {
;     extern __shared__ __attribute__((aligned(16))) unsigned char lds_raw[];
;     LAS unsigned char* lds = (LAS unsigned char*)lds_raw;
;     unsigned char* ws = a.ws;
;     stat_t* RS = (stat_t*)(ws + WS_RS); stat_t* RSV = RS + 9 * M;
;     bf16* XB = (bf16*)(ws + WS_XB); bf16* ACT = (bf16*)(ws + WS_ACT); unsigned char* R = ws + WS_R;
;     const int G = gridDim.x;
;     if (threadIdx.x < 4) ((LAS unsigned*)(lds + BARST_OFF))[threadIdx.x] = 0u;
;     if (a.ph_lo == 0 && blockIdx.x == 0) { unsigned* bw = (unsigned*)(ws + WS_BAR); for (int i = threadIdx.x; i < XCD_BAR_WORDS; i += NW * 64) bw[i] = 0u; }
;     __syncthreads();
;     XcdBarrier bar; bar.bar = (unsigned*)(ws + WS_BAR); bar.x = 0; bar.st = (volatile LAS unsigned*)(lds + BARST_OFF);
_Z10fwd_kernel4Args:
	s_load_dwordx8 s[4:11], s[0:1], 0x80
	s_load_dwordx2 s[34:35], s[0:1], 0xa0
	s_load_dwordx4 s[20:23], s[0:1], 0xa8
	v_writelane_b32 v252, s2, 0
	s_add_u32 s2, s0, 0xb8
	s_addc_u32 s3, s1, 0
	s_waitcnt lgkmcnt(0)
	v_writelane_b32 v252, s4, 1
	v_and_b32_e32 v246, 0x3ff, v0
	v_readfirstlane_b32 s98, v246
	s_nop 0
	s_bitcmp1_b32 s98, 8
	s_cbranch_scc1 .Lprio_all
	s_setprio 1
